# GEMM K-loops free of VALU address arithmetic: the two remaining LDS read address adds hoisted out of the loops
# baseline (speedup 1.0000x reference)
; #define PG8_STAGE(bufoff, gbase, voff) do { _Pragma("unroll") for (int _i = 0; _i < 2; ++_i) \
;         __builtin_amdgcn_global_load_lds((const unsigned*)((const char*)(gbase) + (voff)[_i]), (LAS unsigned*)(lds + (bufoff) + ldsw + _i * 8192), 16, 0, 0); } while (0)
; #define PG8_WAIT_V(n) asm volatile("s_waitcnt vmcnt(" #n ")" ::: "memory")
; #define PG8_BAR __builtin_amdgcn_s_barrier()
; template <class Epi>
; __device__ __forceinline__ void gemm_phase(LAS unsigned char* lds, const Gemm g, const StaticOrder& S, const Epi& E) {
;     const int tid = threadIdx.x, wid = __builtin_amdgcn_readfirstlane(tid >> 6), lane = tid & 63, wr = wid >> 2, wc = wid & 3, fr = lane & 15, fq = lane >> 4;
;     const int K = g.K, nt = K / BK;
;     unsigned voffA[2], voffB[2];
; #pragma unroll
;     for (int i = 0; i < 2; ++i) { int R, C; stage_rc(tid * 16 + i * 8192, R, C); const int Rb = Epi::PERM ? ((R & ~31) + perm32(R & 31)) : R;
;         voffA[i] = (unsigned)(R * K + C) * 2u; voffB[i] = (unsigned)(Rb * K + C) * 2u; }
;     const size_t kstep = (size_t)(BK * 2);
;     const size_t hstep = (size_t)HALF * K * 2;
;     const size_t tstep = 2 * hstep;
;     const unsigned ldsw = (unsigned)wid * 1024u;
;     const int aoff = lds_byte(wr * 64 + fr, fq * 8), boff = lds_byte(wc * 32 + fr, fq * 8);
;     ...
;     Unit cur, nxt; int ui = 0;
;     if (!S.next(0, cur)) return;
;     f32x4 acc[2][2][4][2];
; #pragma unroll
;     for (int a = 0; a < 2; ++a)
; #pragma unroll
;         for (int b = 0; b < 2; ++b)
; #pragma unroll
;             for (int m = 0; m < 4; ++m)
; #pragma unroll
;                 for (int n = 0; n < 2; ++n) acc[a][b][m][n] = (f32x4){0.f, 0.f, 0.f, 0.f};
;     bf16x8 At[4][2], B0[2][2], B1[2][2];
;     const char* cA = (const char*)g.A + (size_t)cur.pm * tstep; const char* cB = (const char*)g.Bt + (size_t)cur.pn * tstep;
;     PG8_STAGE(PG8_SB(0, 0), cB, voffB); PG8_STAGE(PG8_SA(0, 0), cA, voffA); PG8_STAGE(PG8_SB(0, 1), cB + hstep, voffB); PG8_STAGE(PG8_SA(0, 1), cA + hstep, voffA);
;     if (wr == 1) PG8_BAR;
;     PG8_WAIT_V(4); PG8_BAR;
;     PG8_STAGE(PG8_SB(1, 0), cB + kstep, voffB); PG8_STAGE(PG8_SA(1, 0), cA + kstep, voffA); PG8_STAGE(PG8_SB(1, 1), cB + hstep + kstep, voffB);
;     PG8_WAIT_V(6); PG8_BAR;
.LBB0_75:
	s_mov_b64 s[16:17], 0x80
	s_lshl_b32 s9, s9, 5
	s_add_i32 m0, s42, 0x18000
	v_lshl_add_u64 v[6:7], v[6:7], 0, s[16:17]
	s_lshl_b32 s47, s10, 6
	s_lshl_b32 s7, s10, 13
	s_and_b32 s25, s9, 0x60
	s_waitcnt vmcnt(4)
	s_barrier
	global_load_lds_dwordx4 v[6:7], off
	v_lshl_add_u64 v[4:5], v[4:5], 0, s[16:17]
	s_add_i32 m0, s42, 0x1a000
	s_add_i32 s48, s42, 0x8000
	s_add_i32 s49, s42, 0xa000
	global_load_lds_dwordx4 v[4:5], off
	v_lshl_add_u64 v[2:3], v[2:3], 0, s[16:17]
	s_mov_b32 m0, s48
	s_add_u32 s10, s18, 0x80080
	global_load_lds_dwordx4 v[2:3], off
	v_lshl_add_u64 v[0:1], v[0:1], 0, s[16:17]
	s_mov_b32 m0, s49
	s_addc_u32 s11, s19, 0
	global_load_lds_dwordx4 v[0:1], off
	s_add_i32 m0, s42, 0x1c000
	v_lshl_add_u64 v[0:1], s[10:11], 0, v[140:141]
	global_load_lds_dwordx4 v[0:1], off
	v_lshl_add_u64 v[0:1], s[10:11], 0, v[136:137]
	s_add_i32 m0, s42, 0x1e000
	v_lshlrev_b32_e32 v2, 12, v160
	global_load_lds_dwordx4 v[0:1], off
	v_lshlrev_b32_e32 v1, 2, v161
	v_lshl_or_b32 v0, v161, 6, v162
	v_and_b32_e32 v1, 32, v1
	v_bitop3_b32 v0, v0, s7, v1 bitop3:0xde
	v_lshlrev_b32_e32 v1, 9, v133
	v_and_b32_e32 v1, 0x70000, v1
	s_waitcnt lgkmcnt(0)
	s_add_u32 s22, s12, 0x11100000
	v_or3_b32 v1, v9, v1, v2
	s_addc_u32 s23, s13, 0
	v_add_u32_e32 v146, v1, v159
	v_lshlrev_b32_e32 v1, 5, v8
	s_waitcnt vmcnt(6)
	s_add_u32 s51, s12, 0x1190c800
	v_and_b32_e32 v1, 0xf0000, v1
	v_lshl_or_b32 v135, s25, 7, v163
	s_addc_u32 s52, s13, 0
	v_or3_b32 v1, v9, v1, v2
	s_add_i32 s55, 0, 0x10000
	s_add_i32 s56, 0, 0x14000
	s_sext_i32_i16 s24, s8
	s_mov_b32 s50, 0x8000
	v_cmp_eq_u32_e64 s[8:9], 15, v161
	s_ashr_i32 s53, s38, 31
	s_mov_b32 s54, s38
	v_or_b32_e32 v172, s25, v158
	v_mov_b32_e32 v147, v145
	v_add_u32_e32 v148, v1, v159
	v_mov_b32_e32 v149, v145
	v_mov_b64_e32 v[150:151], 0xf68
	v_mov_b64_e32 v[152:153], 0xf67
	v_add_u32_e32 v173, s55, v135
	v_add_u32_e32 v174, 0, v0
	v_add_u32_e32 v175, s56, v135
	v_add_u32_e32 v236, 0x18000, v135
	v_add_u32_e32 v237, 0x1c000, v135
	s_movk_i32 s57, 0xc80
	s_movk_i32 s58, 0x3a00
	s_movk_i32 s59, 0x7fff
	s_movk_i32 s60, 0x1fff
	s_movk_i32 s61, 0x7f4f
	s_movk_i32 s62, 0x7f50
	s_barrier
	s_branch .LBB0_77

; #define PG8_STAGE(bufoff, gbase, voff) do { _Pragma("unroll") for (int _i = 0; _i < 2; ++_i) \
;         __builtin_amdgcn_global_load_lds((const unsigned*)((const char*)(gbase) + (voff)[_i]), (LAS unsigned*)(lds + (bufoff) + ldsw + _i * 8192), 16, 0, 0); } while (0)
; #define PG8_LDA(dst, b, h) do { _Pragma("unroll") for (int m = 0; m < 4; ++m) _Pragma("unroll") for (int k = 0; k < 2; ++k) dst[m][k] = *(const LAS bf16x8*)(lds + PG8_SA(b, h) + aoff + m * 2048 + k * 1024); } while (0)
; #define PG8_LDB(dst, b, h) do { _Pragma("unroll") for (int n = 0; n < 2; ++n) _Pragma("unroll") for (int k = 0; k < 2; ++k) dst[n][k] = *(const LAS bf16x8*)(lds + PG8_SB(b, h) + boff + n * 2048 + k * 1024); } while (0)
; #define PG8_MMA(ai, bj, At, Bt) do { __builtin_amdgcn_s_setprio(1); _Pragma("unroll") for (int m = 0; m < 4; ++m) _Pragma("unroll") for (int n = 0; n < 2; ++n) _Pragma("unroll") for (int k = 0; k < 2; ++k) \
;         acc[ai][bj][m][n] = __builtin_amdgcn_mfma_f32_16x16x32_bf16(Bt[n][k], At[m][k], acc[ai][bj][m][n], 0, 0, 0); __builtin_amdgcn_s_setprio(0); } while (0)
; #define PG8_WAIT_V(n) asm volatile("s_waitcnt vmcnt(" #n ")" ::: "memory")
; #define PG8_WAIT_L(n) asm volatile("s_waitcnt lgkmcnt(" #n ")" ::: "memory")
; #define PG8_BAR __builtin_amdgcn_s_barrier()
; #define PG8_SCHED __builtin_amdgcn_sched_barrier(0)
; template <class Epi>
; __device__ __forceinline__ void gemm_phase(LAS unsigned char* lds, const Gemm g, const StaticOrder& S, const Epi& E) {
;     ...
;             PG8_LDB(B0, 0, 0); PG8_SCHED; PG8_LDA(At, 0, 0); PG8_STAGE(PG8_SA(1, 1), a1 + hstep, voffA);
;             PG8_WAIT_L(8); PG8_BAR; PG8_WAIT_L(0); PG8_MMA(0, 0, At, B0); PG8_BAR; PG8_SCHED;
;             PG8_LDB(B1, 0, 1); PG8_STAGE(PG8_SB(0, 0), b2, voffB);
;             PG8_BAR; PG8_WAIT_L(0); PG8_MMA(0, 1, At, B1); PG8_BAR;
;             PG8_LDA(At, 0, 1); PG8_STAGE(PG8_SA(0, 0), a2, voffA);
;             PG8_BAR; PG8_WAIT_L(0); PG8_MMA(1, 0, At, B0); PG8_BAR; PG8_SCHED;
;             PG8_STAGE(PG8_SB(0, 1), b2 + hstep, voffB);
;             PG8_WAIT_V(6); PG8_BAR; PG8_MMA(1, 1, At, B1); PG8_BAR;
.LBB0_80:
	ds_read_b128 v[154:157], v173
	ds_read_b128 v[176:179], v173 offset:1024
	ds_read_b128 v[180:183], v173 offset:2048
	ds_read_b128 v[184:187], v173 offset:3072
	s_add_u32 s26, s12, 0xfff80080
	s_addc_u32 s27, s13, -1
	s_cmp_eq_u32 s67, 28
	s_cselect_b32 s29, s7, s27
	s_cselect_b32 s28, s63, s26
	s_cselect_b32 s27, s25, s66
	s_cselect_b32 s26, s64, s65
	s_add_i32 m0, s42, 0xc000
	ds_read_b128 v[188:191], v174
	ds_read_b128 v[192:195], v174 offset:1024
	ds_read_b128 v[196:199], v174 offset:2048
	ds_read_b128 v[200:203], v174 offset:3072
	ds_read_b128 v[204:207], v174 offset:4096
	ds_read_b128 v[208:211], v174 offset:5120
	ds_read_b128 v[212:215], v174 offset:6144
	ds_read_b128 v[216:219], v174 offset:7168
	global_load_lds_dwordx4 v146, s[12:13]
	s_add_i32 m0, s42, 0xe000
	s_nop 0
	global_load_lds_dwordx4 v148, s[12:13]
	s_waitcnt lgkmcnt(8)
	s_barrier
	s_waitcnt lgkmcnt(0)
	s_waitcnt lgkmcnt(0)
	v_mfma_f32_16x16x32_bf16 v[124:127], v[154:157], v[188:191], v[124:127]
	v_mfma_f32_16x16x32_bf16 v[120:123], v[180:183], v[188:191], v[120:123]
	v_mfma_f32_16x16x32_bf16 v[116:119], v[154:157], v[196:199], v[116:119]
	v_mfma_f32_16x16x32_bf16 v[112:115], v[180:183], v[196:199], v[112:115]
	v_mfma_f32_16x16x32_bf16 v[100:103], v[154:157], v[204:207], v[100:103]
	v_mfma_f32_16x16x32_bf16 v[96:99], v[180:183], v[204:207], v[96:99]
	v_mfma_f32_16x16x32_bf16 v[76:79], v[154:157], v[212:215], v[76:79]
	v_mfma_f32_16x16x32_bf16 v[72:75], v[180:183], v[212:215], v[72:75]
	v_mfma_f32_16x16x32_bf16 v[124:127], v[176:179], v[192:195], v[124:127]
	v_mfma_f32_16x16x32_bf16 v[120:123], v[184:187], v[192:195], v[120:123]
	v_mfma_f32_16x16x32_bf16 v[116:119], v[176:179], v[200:203], v[116:119]
	v_mfma_f32_16x16x32_bf16 v[112:115], v[184:187], v[200:203], v[112:115]
	v_mfma_f32_16x16x32_bf16 v[100:103], v[176:179], v[208:211], v[100:103]
	v_mfma_f32_16x16x32_bf16 v[96:99], v[184:187], v[208:211], v[96:99]
	v_mfma_f32_16x16x32_bf16 v[76:79], v[176:179], v[216:219], v[76:79]
	v_mfma_f32_16x16x32_bf16 v[72:75], v[184:187], v[216:219], v[72:75]
	s_barrier
	s_add_i32 s68, s55, s35
	s_add_u32 s72, s26, 0x80
	s_addc_u32 s73, s27, 0
	s_mov_b32 m0, s68
	ds_read_b128 v[220:223], v175
	ds_read_b128 v[224:227], v175 offset:1024
	ds_read_b128 v[228:231], v175 offset:2048
	ds_read_b128 v[232:235], v175 offset:3072
	global_load_lds_dwordx4 v140, s[26:27]
	s_add_i32 m0, s68, 0x2000
	s_nop 0
	global_load_lds_dwordx4 v136, s[26:27]
	s_barrier
	s_waitcnt lgkmcnt(0)
	s_waitcnt lgkmcnt(0)
	v_mfma_f32_16x16x32_bf16 v[108:111], v[220:223], v[188:191], v[108:111]
	v_mfma_f32_16x16x32_bf16 v[104:107], v[228:231], v[188:191], v[104:107]
	v_mfma_f32_16x16x32_bf16 v[92:95], v[220:223], v[196:199], v[92:95]
	v_mfma_f32_16x16x32_bf16 v[88:91], v[228:231], v[196:199], v[88:91]
	v_mfma_f32_16x16x32_bf16 v[84:87], v[220:223], v[204:207], v[84:87]
	v_mfma_f32_16x16x32_bf16 v[80:83], v[228:231], v[204:207], v[80:83]
	v_mfma_f32_16x16x32_bf16 v[68:71], v[220:223], v[212:215], v[68:71]
	v_mfma_f32_16x16x32_bf16 v[64:67], v[228:231], v[212:215], v[64:67]
	v_mfma_f32_16x16x32_bf16 v[108:111], v[224:227], v[192:195], v[108:111]
	v_mfma_f32_16x16x32_bf16 v[104:107], v[232:235], v[192:195], v[104:107]
	v_mfma_f32_16x16x32_bf16 v[92:95], v[224:227], v[200:203], v[92:95]
	v_mfma_f32_16x16x32_bf16 v[88:91], v[232:235], v[200:203], v[88:91]
	v_mfma_f32_16x16x32_bf16 v[84:87], v[224:227], v[208:211], v[84:87]
	v_mfma_f32_16x16x32_bf16 v[80:83], v[232:235], v[208:211], v[80:83]
	v_mfma_f32_16x16x32_bf16 v[68:71], v[224:227], v[216:219], v[68:71]
	v_mfma_f32_16x16x32_bf16 v[64:67], v[232:235], v[216:219], v[64:67]
	s_mov_b32 m0, s42
	s_add_u32 s74, s28, 0x80
	s_addc_u32 s75, s29, 0
	s_barrier
	ds_read_b128 v[188:191], v174 offset:16384
	ds_read_b128 v[192:195], v174 offset:17408
	ds_read_b128 v[196:199], v174 offset:18432
	ds_read_b128 v[200:203], v174 offset:19456
	ds_read_b128 v[204:207], v174 offset:20480
	ds_read_b128 v[208:211], v174 offset:21504
	ds_read_b128 v[212:215], v174 offset:22528
	ds_read_b128 v[216:219], v174 offset:23552
	global_load_lds_dwordx4 v142, s[28:29]
	s_mov_b32 m0, s43
	s_nop 0
	global_load_lds_dwordx4 v138, s[28:29]
	s_barrier
	s_waitcnt lgkmcnt(0)
	s_waitcnt lgkmcnt(0)
	v_mfma_f32_16x16x32_bf16 v[60:63], v[154:157], v[188:191], v[60:63]
	v_mfma_f32_16x16x32_bf16 v[56:59], v[180:183], v[188:191], v[56:59]
	v_mfma_f32_16x16x32_bf16 v[52:55], v[154:157], v[196:199], v[52:55]
	v_mfma_f32_16x16x32_bf16 v[48:51], v[180:183], v[196:199], v[48:51]
	v_mfma_f32_16x16x32_bf16 v[36:39], v[154:157], v[204:207], v[36:39]
	v_mfma_f32_16x16x32_bf16 v[32:35], v[180:183], v[204:207], v[32:35]
	v_mfma_f32_16x16x32_bf16 v[12:15], v[154:157], v[212:215], v[12:15]
	v_mfma_f32_16x16x32_bf16 v[8:11], v[180:183], v[212:215], v[8:11]
	v_mfma_f32_16x16x32_bf16 v[60:63], v[176:179], v[192:195], v[60:63]
	v_mfma_f32_16x16x32_bf16 v[56:59], v[184:187], v[192:195], v[56:59]
	v_mfma_f32_16x16x32_bf16 v[52:55], v[176:179], v[200:203], v[52:55]
	v_mfma_f32_16x16x32_bf16 v[48:51], v[184:187], v[200:203], v[48:51]
	v_mfma_f32_16x16x32_bf16 v[36:39], v[176:179], v[208:211], v[36:39]
	v_mfma_f32_16x16x32_bf16 v[32:35], v[184:187], v[208:211], v[32:35]
	v_mfma_f32_16x16x32_bf16 v[12:15], v[176:179], v[216:219], v[12:15]
	v_mfma_f32_16x16x32_bf16 v[8:11], v[184:187], v[216:219], v[8:11]
	s_barrier
	s_add_u32 s68, s26, 0x80000
	s_addc_u32 s69, s27, 0
	s_add_i32 s70, s56, s35
	s_mov_b32 m0, s70
	s_nop 0
	global_load_lds_dwordx4 v140, s[68:69]
	s_add_i32 m0, s70, 0x2000
	s_nop 0
	global_load_lds_dwordx4 v136, s[68:69]
	s_waitcnt vmcnt(6)
	s_barrier
; #define PG8_STAGE(bufoff, gbase, voff) do { _Pragma("unroll") for (int _i = 0; _i < 2; ++_i) \
;         __builtin_amdgcn_global_load_lds((const unsigned*)((const char*)(gbase) + (voff)[_i]), (LAS unsigned*)(lds + (bufoff) + ldsw + _i * 8192), 16, 0, 0); } while (0)
; #define PG8_LDA(dst, b, h) do { _Pragma("unroll") for (int m = 0; m < 4; ++m) _Pragma("unroll") for (int k = 0; k < 2; ++k) dst[m][k] = *(const LAS bf16x8*)(lds + PG8_SA(b, h) + aoff + m * 2048 + k * 1024); } while (0)
; #define PG8_LDB(dst, b, h) do { _Pragma("unroll") for (int n = 0; n < 2; ++n) _Pragma("unroll") for (int k = 0; k < 2; ++k) dst[n][k] = *(const LAS bf16x8*)(lds + PG8_SB(b, h) + boff + n * 2048 + k * 1024); } while (0)
; #define PG8_MMA(ai, bj, At, Bt) do { __builtin_amdgcn_s_setprio(1); _Pragma("unroll") for (int m = 0; m < 4; ++m) _Pragma("unroll") for (int n = 0; n < 2; ++n) _Pragma("unroll") for (int k = 0; k < 2; ++k) \
;         acc[ai][bj][m][n] = __builtin_amdgcn_mfma_f32_16x16x32_bf16(Bt[n][k], At[m][k], acc[ai][bj][m][n], 0, 0, 0); __builtin_amdgcn_s_setprio(0); } while (0)
; #define PG8_WAIT_V(n) asm volatile("s_waitcnt vmcnt(" #n ")" ::: "memory")
; #define PG8_WAIT_L(n) asm volatile("s_waitcnt lgkmcnt(" #n ")" ::: "memory")
; #define PG8_BAR __builtin_amdgcn_s_barrier()
; #define PG8_SCHED __builtin_amdgcn_sched_barrier(0)
; template <class Epi>
; __device__ __forceinline__ void gemm_phase(LAS unsigned char* lds, const Gemm g, const StaticOrder& S, const Epi& E) {
;     ...
;             PG8_WAIT_V(6); PG8_BAR; PG8_MMA(1, 1, At, B1); PG8_BAR;
;             PG8_LDB(B0, 1, 0); PG8_SCHED; PG8_LDA(At, 1, 0); PG8_STAGE(PG8_SA(0, 1), a2 + hstep, voffA);
;             PG8_WAIT_L(8); PG8_BAR; PG8_WAIT_L(0); PG8_MMA(0, 0, At, B0); PG8_BAR; PG8_SCHED;
;             PG8_LDB(B1, 1, 1); PG8_STAGE(PG8_SB(1, 0), b3, voffB);
;             PG8_BAR; PG8_WAIT_L(0); PG8_MMA(0, 1, At, B1); PG8_BAR;
;             PG8_LDA(At, 1, 1); PG8_STAGE(PG8_SA(1, 0), a3, voffA);
	v_mfma_f32_16x16x32_bf16 v[44:47], v[220:223], v[188:191], v[44:47]
	v_mfma_f32_16x16x32_bf16 v[40:43], v[228:231], v[188:191], v[40:43]
	v_mfma_f32_16x16x32_bf16 v[28:31], v[220:223], v[196:199], v[28:31]
	v_mfma_f32_16x16x32_bf16 v[24:27], v[228:231], v[196:199], v[24:27]
	v_mfma_f32_16x16x32_bf16 v[20:23], v[220:223], v[204:207], v[20:23]
	v_mfma_f32_16x16x32_bf16 v[16:19], v[228:231], v[204:207], v[16:19]
	v_mfma_f32_16x16x32_bf16 v[4:7], v[220:223], v[212:215], v[4:7]
	v_mfma_f32_16x16x32_bf16 v[0:3], v[228:231], v[212:215], v[0:3]
	v_mfma_f32_16x16x32_bf16 v[44:47], v[224:227], v[192:195], v[44:47]
	v_mfma_f32_16x16x32_bf16 v[40:43], v[232:235], v[192:195], v[40:43]
	v_mfma_f32_16x16x32_bf16 v[28:31], v[224:227], v[200:203], v[28:31]
	v_mfma_f32_16x16x32_bf16 v[24:27], v[232:235], v[200:203], v[24:27]
	v_mfma_f32_16x16x32_bf16 v[20:23], v[224:227], v[208:211], v[20:23]
	v_mfma_f32_16x16x32_bf16 v[16:19], v[232:235], v[208:211], v[16:19]
	v_mfma_f32_16x16x32_bf16 v[4:7], v[224:227], v[216:219], v[4:7]
	v_mfma_f32_16x16x32_bf16 v[0:3], v[232:235], v[216:219], v[0:3]
	s_add_i32 s68, 0, 0x18000
	s_barrier
	ds_read_b128 v[154:157], v236
	ds_read_b128 v[176:179], v236 offset:1024
	ds_read_b128 v[180:183], v236 offset:2048
	ds_read_b128 v[184:187], v236 offset:3072
	s_add_u32 s28, s28, 0x80000
	s_addc_u32 s29, s29, 0
	s_mov_b32 m0, s44
	ds_read_b128 v[188:191], v174 offset:32768
	ds_read_b128 v[192:195], v174 offset:33792
	ds_read_b128 v[196:199], v174 offset:34816
	ds_read_b128 v[200:203], v174 offset:35840
	ds_read_b128 v[204:207], v174 offset:36864
	ds_read_b128 v[208:211], v174 offset:37888
	ds_read_b128 v[212:215], v174 offset:38912
	ds_read_b128 v[216:219], v174 offset:39936
	global_load_lds_dwordx4 v142, s[28:29]
	s_mov_b32 m0, s45
	s_nop 0
	global_load_lds_dwordx4 v138, s[28:29]
	s_waitcnt lgkmcnt(8)
	s_barrier
	s_waitcnt lgkmcnt(0)
	s_waitcnt lgkmcnt(0)
	v_mfma_f32_16x16x32_bf16 v[124:127], v[154:157], v[188:191], v[124:127]
	v_mfma_f32_16x16x32_bf16 v[120:123], v[180:183], v[188:191], v[120:123]
	v_mfma_f32_16x16x32_bf16 v[116:119], v[154:157], v[196:199], v[116:119]
	v_mfma_f32_16x16x32_bf16 v[112:115], v[180:183], v[196:199], v[112:115]
	v_mfma_f32_16x16x32_bf16 v[100:103], v[154:157], v[204:207], v[100:103]
	v_mfma_f32_16x16x32_bf16 v[96:99], v[180:183], v[204:207], v[96:99]
	v_mfma_f32_16x16x32_bf16 v[76:79], v[154:157], v[212:215], v[76:79]
	v_mfma_f32_16x16x32_bf16 v[72:75], v[180:183], v[212:215], v[72:75]
	v_mfma_f32_16x16x32_bf16 v[124:127], v[176:179], v[192:195], v[124:127]
	v_mfma_f32_16x16x32_bf16 v[120:123], v[184:187], v[192:195], v[120:123]
	v_mfma_f32_16x16x32_bf16 v[116:119], v[176:179], v[200:203], v[116:119]
	v_mfma_f32_16x16x32_bf16 v[112:115], v[184:187], v[200:203], v[112:115]
	v_mfma_f32_16x16x32_bf16 v[100:103], v[176:179], v[208:211], v[100:103]
	v_mfma_f32_16x16x32_bf16 v[96:99], v[184:187], v[208:211], v[96:99]
	v_mfma_f32_16x16x32_bf16 v[76:79], v[176:179], v[216:219], v[76:79]
	v_mfma_f32_16x16x32_bf16 v[72:75], v[184:187], v[216:219], v[72:75]
	s_barrier
	s_add_i32 s28, 0, 0x1c000
	s_add_i32 s29, s68, s35
	s_mov_b32 m0, s29
	ds_read_b128 v[220:223], v237
	ds_read_b128 v[224:227], v237 offset:1024
	ds_read_b128 v[228:231], v237 offset:2048
	ds_read_b128 v[232:235], v237 offset:3072
	global_load_lds_dwordx4 v140, s[72:73]
	s_add_i32 m0, s29, 0x2000
	s_nop 0
	global_load_lds_dwordx4 v136, s[72:73]
	s_barrier
	s_waitcnt lgkmcnt(0)
	s_waitcnt lgkmcnt(0)
	v_mfma_f32_16x16x32_bf16 v[108:111], v[220:223], v[188:191], v[108:111]
	v_mfma_f32_16x16x32_bf16 v[104:107], v[228:231], v[188:191], v[104:107]
	v_mfma_f32_16x16x32_bf16 v[92:95], v[220:223], v[196:199], v[92:95]
	v_mfma_f32_16x16x32_bf16 v[88:91], v[228:231], v[196:199], v[88:91]
	v_mfma_f32_16x16x32_bf16 v[84:87], v[220:223], v[204:207], v[84:87]
	v_mfma_f32_16x16x32_bf16 v[80:83], v[228:231], v[204:207], v[80:83]
	v_mfma_f32_16x16x32_bf16 v[68:71], v[220:223], v[212:215], v[68:71]
	v_mfma_f32_16x16x32_bf16 v[64:67], v[228:231], v[212:215], v[64:67]
	v_mfma_f32_16x16x32_bf16 v[108:111], v[224:227], v[192:195], v[108:111]
	v_mfma_f32_16x16x32_bf16 v[104:107], v[232:235], v[192:195], v[104:107]
	v_mfma_f32_16x16x32_bf16 v[92:95], v[224:227], v[200:203], v[92:95]
	v_mfma_f32_16x16x32_bf16 v[88:91], v[232:235], v[200:203], v[88:91]
	v_mfma_f32_16x16x32_bf16 v[84:87], v[224:227], v[208:211], v[84:87]
	v_mfma_f32_16x16x32_bf16 v[80:83], v[232:235], v[208:211], v[80:83]
	v_mfma_f32_16x16x32_bf16 v[68:71], v[224:227], v[216:219], v[68:71]
	v_mfma_f32_16x16x32_bf16 v[64:67], v[232:235], v[216:219], v[64:67]
	s_mov_b32 m0, s48
	s_barrier
	ds_read_b128 v[188:191], v174 offset:49152
	ds_read_b128 v[192:195], v174 offset:50176
	ds_read_b128 v[196:199], v174 offset:51200
	ds_read_b128 v[200:203], v174 offset:52224
	ds_read_b128 v[204:207], v174 offset:53248
	ds_read_b128 v[208:211], v174 offset:54272
	ds_read_b128 v[212:215], v174 offset:55296
	ds_read_b128 v[216:219], v174 offset:56320
	global_load_lds_dwordx4 v142, s[74:75]
	s_mov_b32 m0, s49
	s_nop 0
	global_load_lds_dwordx4 v138, s[74:75]
	s_barrier
; __device__ __forceinline__ unsigned pk_bf16(float lo, float hi) { const f32x2 v = (f32x2){lo, hi}; const bf16v2 b = __builtin_convertvector(v, bf16v2); return __builtin_bit_cast(unsigned, b); }
; #define PG8_STAGE(bufoff, gbase, voff) do { _Pragma("unroll") for (int _i = 0; _i < 2; ++_i) \
;         __builtin_amdgcn_global_load_lds((const unsigned*)((const char*)(gbase) + (voff)[_i]), (LAS unsigned*)(lds + (bufoff) + ldsw + _i * 8192), 16, 0, 0); } while (0)
; #define PG8_BAR __builtin_amdgcn_s_barrier()
; template <class Epi>
; __device__ __forceinline__ void gemm_phase(LAS unsigned char* lds, const Gemm g, const StaticOrder& S, const Epi& E) {
;     ...
;             PG8_BAR; PG8_WAIT_L(0); PG8_MMA(0, 1, At, B1); PG8_BAR;
;             PG8_LDA(At, 1, 1); PG8_STAGE(PG8_SA(1, 0), a3, voffA);
;             PG8_BAR; PG8_WAIT_L(0); PG8_MMA(1, 0, At, B0); PG8_BAR; PG8_SCHED;
;             PG8_STAGE(PG8_SB(1, 1), b3 + hstep, voffB);
;             PG8_WAIT_V(6); PG8_BAR; PG8_MMA(1, 1, At, B1); PG8_BAR;
;     __device__ __forceinline__ void operator()(const f32x4 (&acc)[2][2][4][2], const pg8::Unit& u, int wr, int wc, int fr, int fq) const {
;         const int row0 = u.pm * 256 + wr * 64 + fr, col0 = u.pn * 256 + wc * 32 + 8 * fq;
; #pragma unroll
;         for (int ai = 0; ai < 2; ++ai)
; #pragma unroll
;             for (int m = 0; m < 4; ++m) {
;                 const int row = row0 + ai * 128 + m * 16;
;                 bf16_t* rowp = Z + (size_t)row * LDZ + col0;
;                 const bool last = ((row & 63) == 63) && (row >= MP || (row & (SEQ - 1)) == SEQ - 1);
; #pragma unroll
;                 for (int bj = 0; bj < 2; ++bj) {
;                     const f32x4 v0 = acc[ai][bj][m][0], v1 = acc[ai][bj][m][1];
;                     u32x4 w; w.x = pk_bf16(v0[0], v0[1]); w.y = pk_bf16(v0[2], v0[3]); w.z = pk_bf16(v1[0], v1[1]); w.w = pk_bf16(v1[2], v1[3]);
;                     *(u32x4*)(rowp + bj * 128) = w;
;                     if (last) {
;                         const int c = col0 + bj * 128 - ZC_S;
;                         if (c >= 0 && c < NSHIFT) {
;                             float* o = row < MP ? out + O_SHP + (size_t)(row >> 13) * NSHIFT + c : out + O_SHS + (size_t)((row - MP) >> 6) * NSHIFT + c;
;                             *(f32x4*)o = v0; *(f32x4*)(o + 4) = v1;
;                         }
;                     }
;                 }
	s_waitcnt lgkmcnt(0)
	s_waitcnt lgkmcnt(0)
	v_mfma_f32_16x16x32_bf16 v[60:63], v[154:157], v[188:191], v[60:63]
	v_mfma_f32_16x16x32_bf16 v[56:59], v[180:183], v[188:191], v[56:59]
	v_mfma_f32_16x16x32_bf16 v[52:55], v[154:157], v[196:199], v[52:55]
	v_mfma_f32_16x16x32_bf16 v[48:51], v[180:183], v[196:199], v[48:51]
	v_mfma_f32_16x16x32_bf16 v[36:39], v[154:157], v[204:207], v[36:39]
	v_mfma_f32_16x16x32_bf16 v[32:35], v[180:183], v[204:207], v[32:35]
	v_mfma_f32_16x16x32_bf16 v[12:15], v[154:157], v[212:215], v[12:15]
	v_mfma_f32_16x16x32_bf16 v[8:11], v[180:183], v[212:215], v[8:11]
	v_mfma_f32_16x16x32_bf16 v[60:63], v[176:179], v[192:195], v[60:63]
	v_mfma_f32_16x16x32_bf16 v[56:59], v[184:187], v[192:195], v[56:59]
	v_mfma_f32_16x16x32_bf16 v[52:55], v[176:179], v[200:203], v[52:55]
	v_mfma_f32_16x16x32_bf16 v[48:51], v[184:187], v[200:203], v[48:51]
	v_mfma_f32_16x16x32_bf16 v[36:39], v[176:179], v[208:211], v[36:39]
	v_mfma_f32_16x16x32_bf16 v[32:35], v[184:187], v[208:211], v[32:35]
	v_mfma_f32_16x16x32_bf16 v[12:15], v[176:179], v[216:219], v[12:15]
	v_mfma_f32_16x16x32_bf16 v[8:11], v[184:187], v[216:219], v[8:11]
	s_barrier
	s_add_u32 s26, s26, 0x80080
	s_addc_u32 s27, s27, 0
	s_add_i32 s28, s28, s35
	s_mov_b32 m0, s28
	s_nop 0
	global_load_lds_dwordx4 v140, s[26:27]
	s_add_i32 m0, s28, 0x2000
	s_nop 0
	global_load_lds_dwordx4 v136, s[26:27]
	s_waitcnt vmcnt(6)
	s_barrier
	v_mfma_f32_16x16x32_bf16 v[44:47], v[220:223], v[188:191], v[44:47]
	v_mfma_f32_16x16x32_bf16 v[40:43], v[228:231], v[188:191], v[40:43]
	v_mfma_f32_16x16x32_bf16 v[28:31], v[220:223], v[196:199], v[28:31]
	v_mfma_f32_16x16x32_bf16 v[24:27], v[228:231], v[196:199], v[24:27]
	v_mfma_f32_16x16x32_bf16 v[20:23], v[220:223], v[204:207], v[20:23]
	v_mfma_f32_16x16x32_bf16 v[16:19], v[228:231], v[204:207], v[16:19]
	v_mfma_f32_16x16x32_bf16 v[4:7], v[220:223], v[212:215], v[4:7]
	v_mfma_f32_16x16x32_bf16 v[0:3], v[228:231], v[212:215], v[0:3]
	v_mfma_f32_16x16x32_bf16 v[44:47], v[224:227], v[192:195], v[44:47]
	v_mfma_f32_16x16x32_bf16 v[40:43], v[232:235], v[192:195], v[40:43]
	v_mfma_f32_16x16x32_bf16 v[28:31], v[224:227], v[200:203], v[28:31]
	v_mfma_f32_16x16x32_bf16 v[24:27], v[232:235], v[200:203], v[24:27]
	v_mfma_f32_16x16x32_bf16 v[20:23], v[224:227], v[208:211], v[20:23]
	v_mfma_f32_16x16x32_bf16 v[16:19], v[232:235], v[208:211], v[16:19]
	v_mfma_f32_16x16x32_bf16 v[4:7], v[224:227], v[216:219], v[4:7]
	v_mfma_f32_16x16x32_bf16 v[0:3], v[232:235], v[216:219], v[0:3]
	s_add_i32 s67, s67, 2
	s_add_u32 s12, s12, 0x100
	s_addc_u32 s13, s13, 0
	s_add_u32 s65, s65, 0x100
	s_addc_u32 s66, s66, 0
	s_cmp_gt_u32 s67, 29
	s_barrier
	s_cbranch_scc0 .LBB0_80
	s_lshl_b32 s7, s31, 8
	s_add_i32 s7, s7, s47
	v_lshl_or_b32 v156, s30, 8, v172
	s_add_i32 s12, s7, 0xffff8000
	v_or_b32_e32 v176, s7, v161
	v_ashrrev_i32_e32 v157, 31, v156
	s_lshr_b32 s63, s12, 6
	s_ashr_i32 s12, s7, 13
	v_mov_b64_e32 v[178:179], s[14:15]
	s_mul_i32 s26, s12, 0xc80
	v_mad_i64_i32 v[180:181], s[12:13], v176, s58, v[178:179]
	v_lshlrev_b64 v[154:155], 1, v[156:157]
	v_cvt_pk_bf16_f32 v108, v108, v109
	v_cvt_pk_bf16_f32 v109, v110, v111
	v_cvt_pk_bf16_f32 v110, v104, v105
	v_or_b32_e32 v104, 16, v176
	v_cvt_pk_bf16_f32 v92, v92, v93
	v_cvt_pk_bf16_f32 v93, v94, v95
	v_cvt_pk_bf16_f32 v94, v88, v89
	v_or_b32_e32 v88, 32, v176
	v_cvt_pk_bf16_f32 v84, v84, v85
	v_cvt_pk_bf16_f32 v85, v86, v87
	v_cvt_pk_bf16_f32 v87, v82, v83
	v_or_b32_e32 v82, 48, v176
	v_lshl_add_u64 v[180:181], v[180:181], 0, v[154:155]
	v_cvt_pk_bf16_f32 v111, v106, v107
	v_mad_i64_i32 v[104:105], s[12:13], v104, s58, v[178:179]
	v_mad_i64_i32 v[88:89], s[12:13], v88, s58, v[178:179]
	v_cvt_pk_bf16_f32 v86, v80, v81
	v_mad_i64_i32 v[80:81], s[12:13], v82, s58, v[178:179]
	v_bitop3_b32 v83, v176, s60, 48 bitop3:0xc8
	global_store_dwordx4 v[180:181], v[108:111], off offset:256
	v_cvt_pk_bf16_f32 v95, v90, v91
	v_cmp_lt_i32_e32 vcc, s59, v82
	v_lshl_add_u64 v[108:109], v[104:105], 0, v[154:155]
	v_cmp_eq_u32_e64 s[12:13], s60, v83
	global_store_dwordx4 v[108:109], v[92:95], off offset:256
	s_or_b64 s[12:13], vcc, s[12:13]
	s_mul_hi_u32 s25, s63, 0x3200
	v_lshl_add_u64 v[92:93], v[88:89], 0, v[154:155]
	s_mulk_i32 s63, 0x3200
	s_ashr_i32 s27, s26, 31
	v_cvt_pk_bf16_f32 v124, v124, v125
	v_cvt_pk_bf16_f32 v125, v126, v127
	v_cvt_pk_bf16_f32 v126, v120, v121
	v_cvt_pk_bf16_f32 v127, v122, v123
	v_cvt_pk_bf16_f32 v104, v116, v117
	v_cvt_pk_bf16_f32 v105, v118, v119
	v_cvt_pk_bf16_f32 v106, v112, v113
	v_cvt_pk_bf16_f32 v107, v114, v115
	v_cvt_pk_bf16_f32 v88, v100, v101
	v_cvt_pk_bf16_f32 v89, v102, v103
	v_cvt_pk_bf16_f32 v90, v96, v97
	v_cvt_pk_bf16_f32 v91, v98, v99
	global_store_dwordx4 v[92:93], v[84:87], off offset:256
	v_lshl_add_u64 v[80:81], v[80:81], 0, v[154:155]
	s_and_b64 s[28:29], s[8:9], s[12:13]
	v_cmp_gt_i32_e32 vcc, s50, v82
	v_cvt_pk_bf16_f32 v82, v76, v77
	v_cvt_pk_bf16_f32 v83, v78, v79
	v_cvt_pk_bf16_f32 v84, v72, v73
	v_cvt_pk_bf16_f32 v85, v74, v75
	v_add_u32_e32 v144, 0xfffff400, v156
	global_store_dwordx4 v[180:181], v[124:127], off
	global_store_dwordx4 v[108:109], v[104:107], off
	global_store_dwordx4 v[92:93], v[88:91], off
	global_store_dwordx4 v[80:81], v[82:85], off
	s_and_saveexec_b64 s[30:31], s[28:29]
	s_cbranch_execz .LBB0_84
	v_cmp_gt_u32_e64 s[12:13], s57, v144
	s_and_b64 exec, exec, s[12:13]
	s_cbranch_execz .LBB0_84
	s_lshl_b64 s[12:13], s[26:27], 2
	s_add_u32 s12, s22, s12
	s_addc_u32 s13, s23, s13
	s_add_u32 s64, s51, s63
	s_addc_u32 s65, s52, s25
	v_mov_b32_e32 v82, s65
	v_mov_b32_e32 v83, s13
	v_cndmask_b32_e32 v83, v82, v83, vcc
	v_mov_b32_e32 v82, s64
	v_mov_b32_e32 v84, s12
	v_cndmask_b32_e32 v82, v82, v84, vcc
	v_lshl_add_u64 v[82:83], v[144:145], 2, v[82:83]
	global_store_dwordx4 v[82:83], v[76:79], off
	global_store_dwordx4 v[82:83], v[72:75], off offset:16

; #define PG8_STAGE(bufoff, gbase, voff) do { _Pragma("unroll") for (int _i = 0; _i < 2; ++_i) \
;         __builtin_amdgcn_global_load_lds((const unsigned*)((const char*)(gbase) + (voff)[_i]), (LAS unsigned*)(lds + (bufoff) + ldsw + _i * 8192), 16, 0, 0); } while (0)
; #define PG8_WAIT_V(n) asm volatile("s_waitcnt vmcnt(" #n ")" ::: "memory")
; #define PG8_BAR __builtin_amdgcn_s_barrier()
; template <class Epi>
; __device__ __forceinline__ void gemm_phase(LAS unsigned char* lds, const Gemm g, const StaticOrder& S, const Epi& E) {
;     const int tid = threadIdx.x, wid = __builtin_amdgcn_readfirstlane(tid >> 6), lane = tid & 63, wr = wid >> 2, wc = wid & 3, fr = lane & 15, fq = lane >> 4;
;     const int K = g.K, nt = K / BK;
;     unsigned voffA[2], voffB[2];
; #pragma unroll
;     for (int i = 0; i < 2; ++i) { int R, C; stage_rc(tid * 16 + i * 8192, R, C); const int Rb = Epi::PERM ? ((R & ~31) + perm32(R & 31)) : R;
;         voffA[i] = (unsigned)(R * K + C) * 2u; voffB[i] = (unsigned)(Rb * K + C) * 2u; }
;     const size_t kstep = (size_t)(BK * 2);
;     const size_t hstep = (size_t)HALF * K * 2;
;     const size_t tstep = 2 * hstep;
;     const unsigned ldsw = (unsigned)wid * 1024u;
;     const int aoff = lds_byte(wr * 64 + fr, fq * 8), boff = lds_byte(wc * 32 + fr, fq * 8);
;     ...
;     Unit cur, nxt; int ui = 0;
;     if (!S.next(0, cur)) return;
;     f32x4 acc[2][2][4][2];
; #pragma unroll
;     for (int a = 0; a < 2; ++a)
; #pragma unroll
;         for (int b = 0; b < 2; ++b)
; #pragma unroll
;             for (int m = 0; m < 4; ++m)
; #pragma unroll
;                 for (int n = 0; n < 2; ++n) acc[a][b][m][n] = (f32x4){0.f, 0.f, 0.f, 0.f};
;     bf16x8 At[4][2], B0[2][2], B1[2][2];
;     const char* cA = (const char*)g.A + (size_t)cur.pm * tstep; const char* cB = (const char*)g.Bt + (size_t)cur.pn * tstep;
;     PG8_STAGE(PG8_SB(0, 0), cB, voffB); PG8_STAGE(PG8_SA(0, 0), cA, voffA); PG8_STAGE(PG8_SB(0, 1), cB + hstep, voffB); PG8_STAGE(PG8_SA(0, 1), cA + hstep, voffA);
;     if (wr == 1) PG8_BAR;
;     PG8_WAIT_V(4); PG8_BAR;
;     PG8_STAGE(PG8_SB(1, 0), cB + kstep, voffB); PG8_STAGE(PG8_SA(1, 0), cA + kstep, voffA); PG8_STAGE(PG8_SB(1, 1), cB + hstep + kstep, voffB);
;     PG8_WAIT_V(6); PG8_BAR;
.LBB0_555:
	s_lshl_b32 s12, s12, 5
	s_and_b32 s17, s12, 0x60
	s_mov_b64 s[12:13], 0x80
	s_add_i32 m0, s21, 0x18000
	v_lshl_add_u64 v[6:7], v[6:7], 0, s[12:13]
	s_lshl_b32 s16, s9, 13
	s_waitcnt vmcnt(4)
	s_barrier
	global_load_lds_dwordx4 v[6:7], off
	v_lshl_add_u64 v[4:5], v[4:5], 0, s[12:13]
	s_add_i32 m0, s21, 0x1a000
	s_add_i32 s50, s21, 0x8000
	s_add_i32 s51, s21, 0xa000
	global_load_lds_dwordx4 v[4:5], off
	v_lshl_add_u64 v[2:3], v[2:3], 0, s[12:13]
	s_mov_b32 m0, s50
	s_add_u32 s14, s34, 0x80080
	global_load_lds_dwordx4 v[2:3], off
	v_lshl_add_u64 v[0:1], v[0:1], 0, s[12:13]
	s_mov_b32 m0, s51
	s_addc_u32 s15, s35, 0
	global_load_lds_dwordx4 v[0:1], off
	s_add_i32 m0, s21, 0x1c000
	v_lshl_add_u64 v[0:1], s[14:15], 0, v[138:139]
	global_load_lds_dwordx4 v[0:1], off
	v_lshl_add_u64 v[0:1], s[14:15], 0, v[134:135]
	s_add_i32 m0, s21, 0x1e000
	v_lshlrev_b32_e32 v2, 12, v160
	global_load_lds_dwordx4 v[0:1], off
	v_lshlrev_b32_e32 v1, 2, v161
	v_lshl_or_b32 v0, v161, 6, v162
	v_and_b32_e32 v1, 32, v1
	v_bitop3_b32 v0, v0, s16, v1 bitop3:0xde
	v_lshlrev_b32_e32 v1, 9, v133
	v_and_b32_e32 v1, 0x70000, v1
	v_or3_b32 v1, v9, v1, v2
	v_add_u32_e32 v142, v1, v159
	v_lshlrev_b32_e32 v1, 5, v8
	s_waitcnt vmcnt(6)
	v_and_b32_e32 v1, 0xf0000, v1
	v_lshl_or_b32 v151, s17, 7, v163
	v_or3_b32 v1, v9, v1, v2
	s_add_i32 s54, 0, 0x10000
	s_add_i32 s55, 0, 0x14000
	s_sext_i32_i8 s60, s8
	v_lshl_or_b32 v150, s9, 6, v161
	s_ashr_i32 s52, s38, 31
	s_mov_b32 s53, s38
	v_or_b32_e32 v152, s17, v158
	v_mov_b32_e32 v143, v139
	v_add_u32_e32 v144, v1, v159
	v_mov_b32_e32 v145, v139
	v_mov_b64_e32 v[146:147], 0x440
	v_mov_b64_e32 v[148:149], 0x43f
	v_add_u32_e32 v133, s54, v151
	v_add_u32_e32 v153, 0, v0
	v_add_u32_e32 v154, s55, v151
	v_add_u32_e32 v220, 0x18000, v151
	v_add_u32_e32 v221, 0x1c000, v151
	s_mov_b32 s56, 0x80000
	s_mov_b64 s[14:15], 0x90000
	s_mov_b32 s57, 0x90000
	s_mov_b64 s[16:17], 0xa0000
	s_mov_b32 s58, 0xa0000
	s_mov_b64 s[18:19], 0xb0000
	s_mov_b32 s59, 0xb0000
	s_barrier

; #define PG8_STAGE(bufoff, gbase, voff) do { _Pragma("unroll") for (int _i = 0; _i < 2; ++_i) \
;         __builtin_amdgcn_global_load_lds((const unsigned*)((const char*)(gbase) + (voff)[_i]), (LAS unsigned*)(lds + (bufoff) + ldsw + _i * 8192), 16, 0, 0); } while (0)
; #define PG8_LDA(dst, b, h) do { _Pragma("unroll") for (int m = 0; m < 4; ++m) _Pragma("unroll") for (int k = 0; k < 2; ++k) dst[m][k] = *(const LAS bf16x8*)(lds + PG8_SA(b, h) + aoff + m * 2048 + k * 1024); } while (0)
; #define PG8_LDB(dst, b, h) do { _Pragma("unroll") for (int n = 0; n < 2; ++n) _Pragma("unroll") for (int k = 0; k < 2; ++k) dst[n][k] = *(const LAS bf16x8*)(lds + PG8_SB(b, h) + boff + n * 2048 + k * 1024); } while (0)
; #define PG8_WAIT_V(n) asm volatile("s_waitcnt vmcnt(" #n ")" ::: "memory")
; #define PG8_WAIT_L(n) asm volatile("s_waitcnt lgkmcnt(" #n ")" ::: "memory")
; #define PG8_BAR __builtin_amdgcn_s_barrier()
; #define PG8_SCHED __builtin_amdgcn_sched_barrier(0)
; template <class Epi>
; __device__ __forceinline__ void gemm_phase(LAS unsigned char* lds, const Gemm g, const StaticOrder& S, const Epi& E) {
;     ...
;         const bool has_next = S.next(ui + 1, nxt);
;         const char* nA = has_next ? (const char*)g.A + (size_t)nxt.pm * tstep : cA; const char* nB = has_next ? (const char*)g.Bt + (size_t)nxt.pn * tstep : cB;
;         for (int t = 0; t < nt; t += 2) {
;             const bool last = (t == nt - 2);
;             const char* a1 = cA + (size_t)(t + 1) * kstep;
;             const char* a2 = last ? nA : cA + (size_t)(t + 2) * kstep; const char* b2 = last ? nB : cB + (size_t)(t + 2) * kstep;
;             const char* a3 = a2 + kstep; const char* b3 = b2 + kstep;
;             PG8_LDB(B0, 0, 0); PG8_SCHED; PG8_LDA(At, 0, 0); PG8_STAGE(PG8_SA(1, 1), a1 + hstep, voffA);
;             PG8_WAIT_L(8); PG8_BAR; PG8_WAIT_L(0); PG8_MMA(0, 0, At, B0); PG8_BAR; PG8_SCHED;
;             PG8_LDB(B1, 0, 1); PG8_STAGE(PG8_SB(0, 0), b2, voffB);
;             PG8_BAR; PG8_WAIT_L(0); PG8_MMA(0, 1, At, B1); PG8_BAR;
;             PG8_LDA(At, 0, 1); PG8_STAGE(PG8_SA(0, 0), a2, voffA);
;             PG8_BAR; PG8_WAIT_L(0); PG8_MMA(1, 0, At, B0); PG8_BAR; PG8_SCHED;
;             PG8_STAGE(PG8_SB(0, 1), b2 + hstep, voffB);
;             PG8_WAIT_V(6); PG8_BAR; PG8_MMA(1, 1, At, B1); PG8_BAR;
.LBB0_559:
	ds_read_b128 v[156:159], v133
	ds_read_b128 v[160:163], v133 offset:1024
	ds_read_b128 v[164:167], v133 offset:2048
	ds_read_b128 v[168:171], v133 offset:3072
	s_add_u32 s34, s30, 0xfff80080
	s_addc_u32 s35, s31, -1
	s_cmp_eq_u32 s65, 28
	s_cselect_b32 s41, s25, s35
	s_cselect_b32 s40, s61, s34
	s_cselect_b32 s35, s23, s64
	s_cselect_b32 s34, s62, s63
	s_add_i32 m0, s21, 0xc000
	ds_read_b128 v[172:175], v153
	ds_read_b128 v[176:179], v153 offset:1024
	ds_read_b128 v[180:183], v153 offset:2048
	ds_read_b128 v[184:187], v153 offset:3072
	ds_read_b128 v[188:191], v153 offset:4096
	ds_read_b128 v[192:195], v153 offset:5120
	ds_read_b128 v[196:199], v153 offset:6144
	ds_read_b128 v[200:203], v153 offset:7168
	global_load_lds_dwordx4 v142, s[30:31]
	s_add_i32 m0, s21, 0xe000
	s_nop 0
	global_load_lds_dwordx4 v144, s[30:31]
	s_waitcnt lgkmcnt(8)
	s_barrier
	s_waitcnt lgkmcnt(0)
	s_waitcnt lgkmcnt(0)
	v_mfma_f32_16x16x32_bf16 v[124:127], v[156:159], v[172:175], v[124:127]
	v_mfma_f32_16x16x32_bf16 v[120:123], v[164:167], v[172:175], v[120:123]
	v_mfma_f32_16x16x32_bf16 v[116:119], v[156:159], v[180:183], v[116:119]
	v_mfma_f32_16x16x32_bf16 v[112:115], v[164:167], v[180:183], v[112:115]
	v_mfma_f32_16x16x32_bf16 v[100:103], v[156:159], v[188:191], v[100:103]
	v_mfma_f32_16x16x32_bf16 v[96:99], v[164:167], v[188:191], v[96:99]
	v_mfma_f32_16x16x32_bf16 v[84:87], v[156:159], v[196:199], v[84:87]
	v_mfma_f32_16x16x32_bf16 v[80:83], v[164:167], v[196:199], v[80:83]
	v_mfma_f32_16x16x32_bf16 v[124:127], v[160:163], v[176:179], v[124:127]
	v_mfma_f32_16x16x32_bf16 v[120:123], v[168:171], v[176:179], v[120:123]
	v_mfma_f32_16x16x32_bf16 v[116:119], v[160:163], v[184:187], v[116:119]
	v_mfma_f32_16x16x32_bf16 v[112:115], v[168:171], v[184:187], v[112:115]
	v_mfma_f32_16x16x32_bf16 v[100:103], v[160:163], v[192:195], v[100:103]
	v_mfma_f32_16x16x32_bf16 v[96:99], v[168:171], v[192:195], v[96:99]
	v_mfma_f32_16x16x32_bf16 v[84:87], v[160:163], v[200:203], v[84:87]
	v_mfma_f32_16x16x32_bf16 v[80:83], v[168:171], v[200:203], v[80:83]
	s_barrier
	s_add_i32 s66, s54, s43
	s_add_u32 s72, s34, 0x80
	s_addc_u32 s73, s35, 0
	s_mov_b32 m0, s66
	ds_read_b128 v[204:207], v154
	ds_read_b128 v[208:211], v154 offset:1024
	ds_read_b128 v[212:215], v154 offset:2048
	ds_read_b128 v[216:219], v154 offset:3072
	global_load_lds_dwordx4 v138, s[34:35]
	s_add_i32 m0, s66, 0x2000
	s_nop 0
	global_load_lds_dwordx4 v134, s[34:35]
	s_barrier
	s_waitcnt lgkmcnt(0)
	s_waitcnt lgkmcnt(0)
	v_mfma_f32_16x16x32_bf16 v[108:111], v[204:207], v[172:175], v[108:111]
	v_mfma_f32_16x16x32_bf16 v[104:107], v[212:215], v[172:175], v[104:107]
	v_mfma_f32_16x16x32_bf16 v[92:95], v[204:207], v[180:183], v[92:95]
	v_mfma_f32_16x16x32_bf16 v[88:91], v[212:215], v[180:183], v[88:91]
	v_mfma_f32_16x16x32_bf16 v[76:79], v[204:207], v[188:191], v[76:79]
	v_mfma_f32_16x16x32_bf16 v[72:75], v[212:215], v[188:191], v[72:75]
	v_mfma_f32_16x16x32_bf16 v[68:71], v[204:207], v[196:199], v[68:71]
	v_mfma_f32_16x16x32_bf16 v[64:67], v[212:215], v[196:199], v[64:67]
	v_mfma_f32_16x16x32_bf16 v[108:111], v[208:211], v[176:179], v[108:111]
	v_mfma_f32_16x16x32_bf16 v[104:107], v[216:219], v[176:179], v[104:107]
	v_mfma_f32_16x16x32_bf16 v[92:95], v[208:211], v[184:187], v[92:95]
	v_mfma_f32_16x16x32_bf16 v[88:91], v[216:219], v[184:187], v[88:91]
	v_mfma_f32_16x16x32_bf16 v[76:79], v[208:211], v[192:195], v[76:79]
	v_mfma_f32_16x16x32_bf16 v[72:75], v[216:219], v[192:195], v[72:75]
	v_mfma_f32_16x16x32_bf16 v[68:71], v[208:211], v[200:203], v[68:71]
	v_mfma_f32_16x16x32_bf16 v[64:67], v[216:219], v[200:203], v[64:67]
	s_mov_b32 m0, s21
	s_add_u32 s74, s40, 0x80
	s_addc_u32 s75, s41, 0
	s_barrier
	ds_read_b128 v[172:175], v153 offset:16384
	ds_read_b128 v[176:179], v153 offset:17408
	ds_read_b128 v[180:183], v153 offset:18432
	ds_read_b128 v[184:187], v153 offset:19456
	ds_read_b128 v[188:191], v153 offset:20480
	ds_read_b128 v[192:195], v153 offset:21504
	ds_read_b128 v[196:199], v153 offset:22528
	ds_read_b128 v[200:203], v153 offset:23552
	global_load_lds_dwordx4 v140, s[40:41]
	s_mov_b32 m0, s46
	s_nop 0
	global_load_lds_dwordx4 v136, s[40:41]
	s_barrier
	s_waitcnt lgkmcnt(0)
	s_waitcnt lgkmcnt(0)
	v_mfma_f32_16x16x32_bf16 v[60:63], v[156:159], v[172:175], v[60:63]
	v_mfma_f32_16x16x32_bf16 v[56:59], v[164:167], v[172:175], v[56:59]
	v_mfma_f32_16x16x32_bf16 v[52:55], v[156:159], v[180:183], v[52:55]
	v_mfma_f32_16x16x32_bf16 v[48:51], v[164:167], v[180:183], v[48:51]
	v_mfma_f32_16x16x32_bf16 v[36:39], v[156:159], v[188:191], v[36:39]
	v_mfma_f32_16x16x32_bf16 v[32:35], v[164:167], v[188:191], v[32:35]
	v_mfma_f32_16x16x32_bf16 v[20:23], v[156:159], v[196:199], v[20:23]
	v_mfma_f32_16x16x32_bf16 v[16:19], v[164:167], v[196:199], v[16:19]
	v_mfma_f32_16x16x32_bf16 v[60:63], v[160:163], v[176:179], v[60:63]
	v_mfma_f32_16x16x32_bf16 v[56:59], v[168:171], v[176:179], v[56:59]
	v_mfma_f32_16x16x32_bf16 v[52:55], v[160:163], v[184:187], v[52:55]
	v_mfma_f32_16x16x32_bf16 v[48:51], v[168:171], v[184:187], v[48:51]
	v_mfma_f32_16x16x32_bf16 v[36:39], v[160:163], v[192:195], v[36:39]
	v_mfma_f32_16x16x32_bf16 v[32:35], v[168:171], v[192:195], v[32:35]
	v_mfma_f32_16x16x32_bf16 v[20:23], v[160:163], v[200:203], v[20:23]
	v_mfma_f32_16x16x32_bf16 v[16:19], v[168:171], v[200:203], v[16:19]
	s_barrier
	s_add_u32 s66, s34, 0x80000
	s_addc_u32 s67, s35, 0
	s_add_i32 s68, s55, s43
	s_mov_b32 m0, s68
	s_nop 0
	global_load_lds_dwordx4 v138, s[66:67]
	s_add_i32 m0, s68, 0x2000
	s_nop 0
	global_load_lds_dwordx4 v134, s[66:67]
	s_waitcnt vmcnt(6)
	s_barrier
; #define PG8_STAGE(bufoff, gbase, voff) do { _Pragma("unroll") for (int _i = 0; _i < 2; ++_i) \
;         __builtin_amdgcn_global_load_lds((const unsigned*)((const char*)(gbase) + (voff)[_i]), (LAS unsigned*)(lds + (bufoff) + ldsw + _i * 8192), 16, 0, 0); } while (0)
; #define PG8_LDA(dst, b, h) do { _Pragma("unroll") for (int m = 0; m < 4; ++m) _Pragma("unroll") for (int k = 0; k < 2; ++k) dst[m][k] = *(const LAS bf16x8*)(lds + PG8_SA(b, h) + aoff + m * 2048 + k * 1024); } while (0)
; #define PG8_LDB(dst, b, h) do { _Pragma("unroll") for (int n = 0; n < 2; ++n) _Pragma("unroll") for (int k = 0; k < 2; ++k) dst[n][k] = *(const LAS bf16x8*)(lds + PG8_SB(b, h) + boff + n * 2048 + k * 1024); } while (0)
; #define PG8_MMA(ai, bj, At, Bt) do { __builtin_amdgcn_s_setprio(1); _Pragma("unroll") for (int m = 0; m < 4; ++m) _Pragma("unroll") for (int n = 0; n < 2; ++n) _Pragma("unroll") for (int k = 0; k < 2; ++k) \
;         acc[ai][bj][m][n] = __builtin_amdgcn_mfma_f32_16x16x32_bf16(Bt[n][k], At[m][k], acc[ai][bj][m][n], 0, 0, 0); __builtin_amdgcn_s_setprio(0); } while (0)
; #define PG8_WAIT_V(n) asm volatile("s_waitcnt vmcnt(" #n ")" ::: "memory")
; #define PG8_WAIT_L(n) asm volatile("s_waitcnt lgkmcnt(" #n ")" ::: "memory")
; #define PG8_BAR __builtin_amdgcn_s_barrier()
; #define PG8_SCHED __builtin_amdgcn_sched_barrier(0)
; template <class Epi>
; __device__ __forceinline__ void gemm_phase(LAS unsigned char* lds, const Gemm g, const StaticOrder& S, const Epi& E) {
;     ...
;             PG8_WAIT_V(6); PG8_BAR; PG8_MMA(1, 1, At, B1); PG8_BAR;
;             PG8_LDB(B0, 1, 0); PG8_SCHED; PG8_LDA(At, 1, 0); PG8_STAGE(PG8_SA(0, 1), a2 + hstep, voffA);
;             PG8_WAIT_L(8); PG8_BAR; PG8_WAIT_L(0); PG8_MMA(0, 0, At, B0); PG8_BAR; PG8_SCHED;
;             PG8_LDB(B1, 1, 1); PG8_STAGE(PG8_SB(1, 0), b3, voffB);
;             PG8_BAR; PG8_WAIT_L(0); PG8_MMA(0, 1, At, B1); PG8_BAR;
;             PG8_LDA(At, 1, 1); PG8_STAGE(PG8_SA(1, 0), a3, voffA);
;             PG8_BAR; PG8_WAIT_L(0); PG8_MMA(1, 0, At, B0); PG8_BAR; PG8_SCHED;
	v_mfma_f32_16x16x32_bf16 v[44:47], v[204:207], v[172:175], v[44:47]
	v_mfma_f32_16x16x32_bf16 v[40:43], v[212:215], v[172:175], v[40:43]
	v_mfma_f32_16x16x32_bf16 v[28:31], v[204:207], v[180:183], v[28:31]
	v_mfma_f32_16x16x32_bf16 v[24:27], v[212:215], v[180:183], v[24:27]
	v_mfma_f32_16x16x32_bf16 v[12:15], v[204:207], v[188:191], v[12:15]
	v_mfma_f32_16x16x32_bf16 v[8:11], v[212:215], v[188:191], v[8:11]
	v_mfma_f32_16x16x32_bf16 v[4:7], v[204:207], v[196:199], v[4:7]
	v_mfma_f32_16x16x32_bf16 v[0:3], v[212:215], v[196:199], v[0:3]
	v_mfma_f32_16x16x32_bf16 v[44:47], v[208:211], v[176:179], v[44:47]
	v_mfma_f32_16x16x32_bf16 v[40:43], v[216:219], v[176:179], v[40:43]
	v_mfma_f32_16x16x32_bf16 v[28:31], v[208:211], v[184:187], v[28:31]
	v_mfma_f32_16x16x32_bf16 v[24:27], v[216:219], v[184:187], v[24:27]
	v_mfma_f32_16x16x32_bf16 v[12:15], v[208:211], v[192:195], v[12:15]
	v_mfma_f32_16x16x32_bf16 v[8:11], v[216:219], v[192:195], v[8:11]
	v_mfma_f32_16x16x32_bf16 v[4:7], v[208:211], v[200:203], v[4:7]
	v_mfma_f32_16x16x32_bf16 v[0:3], v[216:219], v[200:203], v[0:3]
	s_add_i32 s66, 0, 0x18000
	s_barrier
	ds_read_b128 v[156:159], v220
	ds_read_b128 v[160:163], v220 offset:1024
	ds_read_b128 v[164:167], v220 offset:2048
	ds_read_b128 v[168:171], v220 offset:3072
	s_add_u32 s40, s40, 0x80000
	s_addc_u32 s41, s41, 0
	s_mov_b32 m0, s47
	ds_read_b128 v[172:175], v153 offset:32768
	ds_read_b128 v[176:179], v153 offset:33792
	ds_read_b128 v[180:183], v153 offset:34816
	ds_read_b128 v[184:187], v153 offset:35840
	ds_read_b128 v[188:191], v153 offset:36864
	ds_read_b128 v[192:195], v153 offset:37888
	ds_read_b128 v[196:199], v153 offset:38912
	ds_read_b128 v[200:203], v153 offset:39936
	global_load_lds_dwordx4 v140, s[40:41]
	s_mov_b32 m0, s48
	s_nop 0
	global_load_lds_dwordx4 v136, s[40:41]
	s_waitcnt lgkmcnt(8)
	s_barrier
	s_waitcnt lgkmcnt(0)
	s_waitcnt lgkmcnt(0)
	v_mfma_f32_16x16x32_bf16 v[124:127], v[156:159], v[172:175], v[124:127]
	v_mfma_f32_16x16x32_bf16 v[120:123], v[164:167], v[172:175], v[120:123]
	v_mfma_f32_16x16x32_bf16 v[116:119], v[156:159], v[180:183], v[116:119]
	v_mfma_f32_16x16x32_bf16 v[112:115], v[164:167], v[180:183], v[112:115]
	v_mfma_f32_16x16x32_bf16 v[100:103], v[156:159], v[188:191], v[100:103]
	v_mfma_f32_16x16x32_bf16 v[96:99], v[164:167], v[188:191], v[96:99]
	v_mfma_f32_16x16x32_bf16 v[84:87], v[156:159], v[196:199], v[84:87]
	v_mfma_f32_16x16x32_bf16 v[80:83], v[164:167], v[196:199], v[80:83]
	v_mfma_f32_16x16x32_bf16 v[124:127], v[160:163], v[176:179], v[124:127]
	v_mfma_f32_16x16x32_bf16 v[120:123], v[168:171], v[176:179], v[120:123]
	v_mfma_f32_16x16x32_bf16 v[116:119], v[160:163], v[184:187], v[116:119]
	v_mfma_f32_16x16x32_bf16 v[112:115], v[168:171], v[184:187], v[112:115]
	v_mfma_f32_16x16x32_bf16 v[100:103], v[160:163], v[192:195], v[100:103]
	v_mfma_f32_16x16x32_bf16 v[96:99], v[168:171], v[192:195], v[96:99]
	v_mfma_f32_16x16x32_bf16 v[84:87], v[160:163], v[200:203], v[84:87]
	v_mfma_f32_16x16x32_bf16 v[80:83], v[168:171], v[200:203], v[80:83]
	s_barrier
	s_add_i32 s40, 0, 0x1c000
	s_add_i32 s41, s66, s43
	s_mov_b32 m0, s41
	ds_read_b128 v[204:207], v221
	ds_read_b128 v[208:211], v221 offset:1024
	ds_read_b128 v[212:215], v221 offset:2048
	ds_read_b128 v[216:219], v221 offset:3072
	global_load_lds_dwordx4 v138, s[72:73]
	s_add_i32 m0, s41, 0x2000
	s_nop 0
	global_load_lds_dwordx4 v134, s[72:73]
	s_barrier
	s_waitcnt lgkmcnt(0)
	s_waitcnt lgkmcnt(0)
	v_mfma_f32_16x16x32_bf16 v[108:111], v[204:207], v[172:175], v[108:111]
	v_mfma_f32_16x16x32_bf16 v[104:107], v[212:215], v[172:175], v[104:107]
	v_mfma_f32_16x16x32_bf16 v[92:95], v[204:207], v[180:183], v[92:95]
	v_mfma_f32_16x16x32_bf16 v[88:91], v[212:215], v[180:183], v[88:91]
	v_mfma_f32_16x16x32_bf16 v[76:79], v[204:207], v[188:191], v[76:79]
	v_mfma_f32_16x16x32_bf16 v[72:75], v[212:215], v[188:191], v[72:75]
	v_mfma_f32_16x16x32_bf16 v[68:71], v[204:207], v[196:199], v[68:71]
	v_mfma_f32_16x16x32_bf16 v[64:67], v[212:215], v[196:199], v[64:67]
	v_mfma_f32_16x16x32_bf16 v[108:111], v[208:211], v[176:179], v[108:111]
	v_mfma_f32_16x16x32_bf16 v[104:107], v[216:219], v[176:179], v[104:107]
	v_mfma_f32_16x16x32_bf16 v[92:95], v[208:211], v[184:187], v[92:95]
	v_mfma_f32_16x16x32_bf16 v[88:91], v[216:219], v[184:187], v[88:91]
	v_mfma_f32_16x16x32_bf16 v[76:79], v[208:211], v[192:195], v[76:79]
	v_mfma_f32_16x16x32_bf16 v[72:75], v[216:219], v[192:195], v[72:75]
	v_mfma_f32_16x16x32_bf16 v[68:71], v[208:211], v[200:203], v[68:71]
	v_mfma_f32_16x16x32_bf16 v[64:67], v[216:219], v[200:203], v[64:67]
	s_mov_b32 m0, s50
	s_barrier
	ds_read_b128 v[172:175], v153 offset:49152
	ds_read_b128 v[176:179], v153 offset:50176
	ds_read_b128 v[180:183], v153 offset:51200
	ds_read_b128 v[184:187], v153 offset:52224
	ds_read_b128 v[188:191], v153 offset:53248
	ds_read_b128 v[192:195], v153 offset:54272
	ds_read_b128 v[196:199], v153 offset:55296
	ds_read_b128 v[200:203], v153 offset:56320
	global_load_lds_dwordx4 v140, s[74:75]
	s_mov_b32 m0, s51
	s_nop 0
	global_load_lds_dwordx4 v136, s[74:75]
	s_barrier
; #define PG8_STAGE(bufoff, gbase, voff) do { _Pragma("unroll") for (int _i = 0; _i < 2; ++_i) \
;         __builtin_amdgcn_global_load_lds((const unsigned*)((const char*)(gbase) + (voff)[_i]), (LAS unsigned*)(lds + (bufoff) + ldsw + _i * 8192), 16, 0, 0); } while (0)
; #define PG8_LDA(dst, b, h) do { _Pragma("unroll") for (int m = 0; m < 4; ++m) _Pragma("unroll") for (int k = 0; k < 2; ++k) dst[m][k] = *(const LAS bf16x8*)(lds + PG8_SA(b, h) + aoff + m * 2048 + k * 1024); } while (0)
; #define PG8_MMA(ai, bj, At, Bt) do { __builtin_amdgcn_s_setprio(1); _Pragma("unroll") for (int m = 0; m < 4; ++m) _Pragma("unroll") for (int n = 0; n < 2; ++n) _Pragma("unroll") for (int k = 0; k < 2; ++k) \
;         acc[ai][bj][m][n] = __builtin_amdgcn_mfma_f32_16x16x32_bf16(Bt[n][k], At[m][k], acc[ai][bj][m][n], 0, 0, 0); __builtin_amdgcn_s_setprio(0); } while (0)
; #define PG8_WAIT_V(n) asm volatile("s_waitcnt vmcnt(" #n ")" ::: "memory")
; #define PG8_WAIT_L(n) asm volatile("s_waitcnt lgkmcnt(" #n ")" ::: "memory")
; #define PG8_BAR __builtin_amdgcn_s_barrier()
; #define PG8_SCHED __builtin_amdgcn_sched_barrier(0)
; template <class Epi>
; __device__ __forceinline__ void gemm_phase(LAS unsigned char* lds, const Gemm g, const StaticOrder& S, const Epi& E) {
;     ...
;             PG8_BAR; PG8_WAIT_L(0); PG8_MMA(0, 1, At, B1); PG8_BAR;
;             PG8_LDA(At, 1, 1); PG8_STAGE(PG8_SA(1, 0), a3, voffA);
;             PG8_BAR; PG8_WAIT_L(0); PG8_MMA(1, 0, At, B0); PG8_BAR; PG8_SCHED;
;             PG8_STAGE(PG8_SB(1, 1), b3 + hstep, voffB);
;             PG8_WAIT_V(6); PG8_BAR; PG8_MMA(1, 1, At, B1); PG8_BAR;
;         }
	s_waitcnt lgkmcnt(0)
	s_waitcnt lgkmcnt(0)
	v_mfma_f32_16x16x32_bf16 v[60:63], v[156:159], v[172:175], v[60:63]
	v_mfma_f32_16x16x32_bf16 v[56:59], v[164:167], v[172:175], v[56:59]
	v_mfma_f32_16x16x32_bf16 v[52:55], v[156:159], v[180:183], v[52:55]
	v_mfma_f32_16x16x32_bf16 v[48:51], v[164:167], v[180:183], v[48:51]
	v_mfma_f32_16x16x32_bf16 v[36:39], v[156:159], v[188:191], v[36:39]
	v_mfma_f32_16x16x32_bf16 v[32:35], v[164:167], v[188:191], v[32:35]
	v_mfma_f32_16x16x32_bf16 v[20:23], v[156:159], v[196:199], v[20:23]
	v_mfma_f32_16x16x32_bf16 v[16:19], v[164:167], v[196:199], v[16:19]
	v_mfma_f32_16x16x32_bf16 v[60:63], v[160:163], v[176:179], v[60:63]
	v_mfma_f32_16x16x32_bf16 v[56:59], v[168:171], v[176:179], v[56:59]
	v_mfma_f32_16x16x32_bf16 v[52:55], v[160:163], v[184:187], v[52:55]
	v_mfma_f32_16x16x32_bf16 v[48:51], v[168:171], v[184:187], v[48:51]
	v_mfma_f32_16x16x32_bf16 v[36:39], v[160:163], v[192:195], v[36:39]
	v_mfma_f32_16x16x32_bf16 v[32:35], v[168:171], v[192:195], v[32:35]
	v_mfma_f32_16x16x32_bf16 v[20:23], v[160:163], v[200:203], v[20:23]
	v_mfma_f32_16x16x32_bf16 v[16:19], v[168:171], v[200:203], v[16:19]
	s_barrier
	s_add_u32 s34, s34, 0x80080
	s_addc_u32 s35, s35, 0
	s_add_i32 s40, s40, s43
	s_mov_b32 m0, s40
	s_nop 0
	global_load_lds_dwordx4 v138, s[34:35]
	s_add_i32 m0, s40, 0x2000
	s_nop 0
	global_load_lds_dwordx4 v134, s[34:35]
	s_waitcnt vmcnt(6)
	s_barrier
	v_mfma_f32_16x16x32_bf16 v[44:47], v[204:207], v[172:175], v[44:47]
	v_mfma_f32_16x16x32_bf16 v[40:43], v[212:215], v[172:175], v[40:43]
	v_mfma_f32_16x16x32_bf16 v[28:31], v[204:207], v[180:183], v[28:31]
	v_mfma_f32_16x16x32_bf16 v[24:27], v[212:215], v[180:183], v[24:27]
	v_mfma_f32_16x16x32_bf16 v[12:15], v[204:207], v[188:191], v[12:15]
	v_mfma_f32_16x16x32_bf16 v[8:11], v[212:215], v[188:191], v[8:11]
	v_mfma_f32_16x16x32_bf16 v[4:7], v[204:207], v[196:199], v[4:7]
	v_mfma_f32_16x16x32_bf16 v[0:3], v[212:215], v[196:199], v[0:3]
	v_mfma_f32_16x16x32_bf16 v[44:47], v[208:211], v[176:179], v[44:47]
	v_mfma_f32_16x16x32_bf16 v[40:43], v[216:219], v[176:179], v[40:43]
	v_mfma_f32_16x16x32_bf16 v[28:31], v[208:211], v[184:187], v[28:31]
	v_mfma_f32_16x16x32_bf16 v[24:27], v[216:219], v[184:187], v[24:27]
	v_mfma_f32_16x16x32_bf16 v[12:15], v[208:211], v[192:195], v[12:15]
	v_mfma_f32_16x16x32_bf16 v[8:11], v[216:219], v[192:195], v[8:11]
	v_mfma_f32_16x16x32_bf16 v[4:7], v[208:211], v[200:203], v[4:7]
	v_mfma_f32_16x16x32_bf16 v[0:3], v[216:219], v[200:203], v[0:3]
	s_add_i32 s65, s65, 2
	s_add_u32 s30, s30, 0x100
	s_addc_u32 s31, s31, 0
	s_add_u32 s63, s63, 0x100
	s_addc_u32 s64, s64, 0
	s_cmp_gt_u32 s65, 29
	s_barrier
	s_cbranch_scc0 .LBB0_559
; __device__ __forceinline__ unsigned pk_bf16(float lo, float hi) { const f32x2 v = (f32x2){lo, hi}; const bf16v2 b = __builtin_convertvector(v, bf16v2); return __builtin_bit_cast(unsigned, b); }
; #define PG8_MMA(ai, bj, At, Bt) do { __builtin_amdgcn_s_setprio(1); _Pragma("unroll") for (int m = 0; m < 4; ++m) _Pragma("unroll") for (int n = 0; n < 2; ++n) _Pragma("unroll") for (int k = 0; k < 2; ++k) \
;         acc[ai][bj][m][n] = __builtin_amdgcn_mfma_f32_16x16x32_bf16(Bt[n][k], At[m][k], acc[ai][bj][m][n], 0, 0, 0); __builtin_amdgcn_s_setprio(0); } while (0)
; #define PG8_WAIT_V(n) asm volatile("s_waitcnt vmcnt(" #n ")" ::: "memory")
; #define PG8_BAR __builtin_amdgcn_s_barrier()
; template <class Epi>
; __device__ __forceinline__ void gemm_phase(LAS unsigned char* lds, const Gemm g, const StaticOrder& S, const Epi& E) {
;     ...
;             PG8_WAIT_V(6); PG8_BAR; PG8_MMA(1, 1, At, B1); PG8_BAR;
;         }
;         E(acc, cur, wr, wc, fr, fq);
;         if (!has_next) break;
; #pragma unroll
;         for (int a = 0; a < 2; ++a)
; #pragma unroll
;             for (int b = 0; b < 2; ++b)
; #pragma unroll
;                 for (int m = 0; m < 4; ++m)
; #pragma unroll
;                     for (int n = 0; n < 2; ++n) acc[a][b][m][n] = (f32x4){0.f, 0.f, 0.f, 0.f};
;         cur = nxt; cA = nA; cB = nB; ++ui;
;     }
;     PG8_WAIT_V(0);
;     if (wr == 0) PG8_BAR;
;     __device__ __forceinline__ void operator()(const f32x4 (&acc)[2][2][4][2], const pg8::Unit& u, int wr, int wc, int fr, int fq) const {
;         const int row0 = u.pm * 256 + wr * 64 + fr, col0 = u.pn * 256 + wc * 32 + 8 * fq;
; #pragma unroll
;         for (int ai = 0; ai < 2; ++ai)
; #pragma unroll
;             for (int m = 0; m < 4; ++m) {
;                 const int row = row0 + ai * 128 + m * 16;
;                 bf16_t* orow = yb + (size_t)row * DM + col0;
; #pragma unroll
;                 for (int bj = 0; bj < 2; ++bj) {
;                     const f32x4 v0 = acc[ai][bj][m][0], v1 = acc[ai][bj][m][1];
;                     *(u32x4*)(orow + bj * 128) = (u32x4){pk_bf16(v0[0], v0[1]), pk_bf16(v0[2], v0[3]), pk_bf16(v1[0], v1[1]), pk_bf16(v1[2], v1[3])};
;                 }
;             }
	v_lshl_add_u32 v156, s20, 8, v150
	v_lshl_or_b32 v158, s60, 8, v152
	v_ashrrev_i32_e32 v157, 31, v156
	v_ashrrev_i32_e32 v159, 31, v158
	v_lshlrev_b64 v[160:161], 12, v[156:157]
	v_lshl_add_u64 v[160:161], s[6:7], 0, v[160:161]
	v_lshlrev_b64 v[158:159], 1, v[158:159]
	v_lshl_add_u64 v[160:161], v[160:161], 0, v[158:159]
	v_cvt_pk_bf16_f32 v60, v60, v61
	v_cvt_pk_bf16_f32 v61, v62, v63
	v_cvt_pk_bf16_f32 v62, v56, v57
	v_add_co_u32_e32 v56, vcc, s56, v160
	v_cvt_pk_bf16_f32 v68, v68, v69
	v_cvt_pk_bf16_f32 v69, v70, v71
	v_cvt_pk_bf16_f32 v70, v64, v65
	v_lshl_add_u64 v[64:65], v[160:161], 0, s[10:11]
	v_addc_co_u32_e32 v57, vcc, 0, v161, vcc
	v_cvt_pk_bf16_f32 v44, v44, v45
	v_cvt_pk_bf16_f32 v45, v46, v47
	v_cvt_pk_bf16_f32 v46, v40, v41
	v_cvt_pk_bf16_f32 v47, v42, v43
	v_cvt_pk_bf16_f32 v108, v108, v109
	v_cvt_pk_bf16_f32 v109, v110, v111
	v_cvt_pk_bf16_f32 v110, v104, v105
	v_or_b32_e32 v104, 16, v156
	global_store_dwordx4 v[64:65], v[44:47], off offset:256
	v_ashrrev_i32_e32 v105, 31, v104
	v_cvt_pk_bf16_f32 v92, v92, v93
	v_add_co_u32_e32 v46, vcc, s57, v160
	v_cvt_pk_bf16_f32 v93, v94, v95
	v_cvt_pk_bf16_f32 v94, v88, v89
	v_or_b32_e32 v88, 32, v156
	v_lshl_add_u64 v[44:45], v[160:161], 0, s[14:15]
	v_addc_co_u32_e32 v47, vcc, 0, v161, vcc
	v_cvt_pk_bf16_f32 v28, v28, v29
	v_cvt_pk_bf16_f32 v29, v30, v31
	v_cvt_pk_bf16_f32 v30, v24, v25
	v_cvt_pk_bf16_f32 v31, v26, v27
	v_lshlrev_b64 v[104:105], 12, v[104:105]
	v_ashrrev_i32_e32 v89, 31, v88
	v_cvt_pk_bf16_f32 v76, v76, v77
	v_cvt_pk_bf16_f32 v77, v78, v79
	v_cvt_pk_bf16_f32 v78, v72, v73
	v_or_b32_e32 v72, 48, v156
	global_store_dwordx4 v[44:45], v[28:31], off offset:256
	v_cvt_pk_bf16_f32 v111, v106, v107
	v_lshl_add_u64 v[104:105], s[6:7], 0, v[104:105]
	v_add_co_u32_e32 v30, vcc, s58, v160
	v_lshlrev_b64 v[88:89], 12, v[88:89]
	v_ashrrev_i32_e32 v73, 31, v72
	v_lshl_add_u64 v[28:29], v[160:161], 0, s[16:17]
	v_addc_co_u32_e32 v31, vcc, 0, v161, vcc
	v_cvt_pk_bf16_f32 v12, v12, v13
	v_cvt_pk_bf16_f32 v13, v14, v15
	v_cvt_pk_bf16_f32 v14, v8, v9
	v_cvt_pk_bf16_f32 v15, v10, v11
	global_store_dwordx4 v[160:161], v[108:111], off offset:256
	v_cvt_pk_bf16_f32 v95, v90, v91
	v_lshl_add_u64 v[88:89], s[6:7], 0, v[88:89]
	v_lshl_add_u64 v[108:109], v[104:105], 0, v[158:159]
	v_lshlrev_b64 v[72:73], 12, v[72:73]
	global_store_dwordx4 v[28:29], v[12:15], off offset:256
	global_store_dwordx4 v[108:109], v[92:95], off offset:256
	v_cvt_pk_bf16_f32 v79, v74, v75
	v_add_co_u32_e32 v14, vcc, s59, v160
	v_lshl_add_u64 v[92:93], v[88:89], 0, v[158:159]
	v_lshl_add_u64 v[72:73], s[6:7], 0, v[72:73]
	v_addc_co_u32_e32 v15, vcc, 0, v161, vcc
	v_cvt_pk_bf16_f32 v124, v124, v125
	v_cvt_pk_bf16_f32 v125, v126, v127
	v_cvt_pk_bf16_f32 v126, v120, v121
	v_cvt_pk_bf16_f32 v127, v122, v123
	v_cvt_pk_bf16_f32 v104, v116, v117
	v_cvt_pk_bf16_f32 v105, v118, v119
	v_cvt_pk_bf16_f32 v106, v112, v113
	v_cvt_pk_bf16_f32 v107, v114, v115
	v_cvt_pk_bf16_f32 v88, v100, v101
	v_cvt_pk_bf16_f32 v89, v102, v103
	v_cvt_pk_bf16_f32 v90, v96, v97
	v_cvt_pk_bf16_f32 v91, v98, v99
	global_store_dwordx4 v[92:93], v[76:79], off offset:256
	v_cvt_pk_bf16_f32 v74, v80, v81
	v_cvt_pk_bf16_f32 v75, v82, v83
	v_lshl_add_u64 v[76:77], v[72:73], 0, v[158:159]
	v_cvt_pk_bf16_f32 v72, v84, v85
	v_cvt_pk_bf16_f32 v73, v86, v87
	v_cvt_pk_bf16_f32 v71, v66, v67
	v_cvt_pk_bf16_f32 v63, v58, v59
	v_cvt_pk_bf16_f32 v40, v52, v53
	v_cvt_pk_bf16_f32 v41, v54, v55
	v_cvt_pk_bf16_f32 v42, v48, v49
	v_cvt_pk_bf16_f32 v43, v50, v51
	v_cvt_pk_bf16_f32 v24, v36, v37
	v_cvt_pk_bf16_f32 v25, v38, v39
	v_cvt_pk_bf16_f32 v26, v32, v33
	v_cvt_pk_bf16_f32 v27, v34, v35
	v_lshl_add_u64 v[12:13], v[160:161], 0, s[18:19]
	v_cvt_pk_bf16_f32 v8, v20, v21
	v_cvt_pk_bf16_f32 v9, v22, v23
	v_cvt_pk_bf16_f32 v10, v16, v17
	v_cvt_pk_bf16_f32 v11, v18, v19
	v_cvt_pk_bf16_f32 v4, v4, v5
	v_cvt_pk_bf16_f32 v5, v6, v7
	v_cvt_pk_bf16_f32 v6, v0, v1
	v_cvt_pk_bf16_f32 v7, v2, v3
	s_and_b64 vcc, exec, s[8:9]
	s_mov_b32 s60, s22
	s_mov_b32 s20, s24
	s_mov_b64 s[34:35], s[28:29]
	s_mov_b64 s[30:31], s[26:27]
	s_mov_b32 s40, s70
	global_store_dwordx4 v[160:161], v[124:127], off
	global_store_dwordx4 v[108:109], v[104:107], off
	global_store_dwordx4 v[92:93], v[88:91], off
	global_store_dwordx4 v[76:77], v[72:75], off
	global_store_dwordx4 v[76:77], v[68:71], off offset:256
	global_store_dwordx4 v[56:57], v[60:63], off
	global_store_dwordx4 v[46:47], v[40:43], off
	global_store_dwordx4 v[30:31], v[24:27], off
	global_store_dwordx4 v[14:15], v[8:11], off
	global_store_dwordx4 v[12:13], v[4:7], off offset:256
	s_cbranch_vccnz .Lg2_exit
	s_cmp_lg_u32 s49, 4
	s_cbranch_scc1 .LBB0_556
	s_waitcnt vmcnt(0)
	s_barrier
	s_lshr_b32 s8, s42, 6
	s_cmp_lg_u32 s8, 4
	s_cbranch_scc1 .LBB0_556
	buffer_wbl2 sc1
	s_waitcnt vmcnt(0)
	s_mov_b64 s[8:9], exec
	s_mov_b64 exec, 1
	v_mov_b32_e32 v0, 0
	v_mov_b32_e32 v1, 1
	global_atomic_add v0, v1, s[36:37] offset:256
	s_mov_b64 exec, s[8:9]
	s_branch .LBB0_556
